# delta_seq chain: B-operand LDS reads issued with the A reads (one LDS latency less per product) + two-stream output epilogue
# baseline (speedup 1.0000x reference)
.Ldq_nopf1:
	ds_read_b128 v[96:99], v171 offset:32768
	ds_read_b128 v[100:103], v171 offset:32784
	ds_read_b128 v[104:107], v171 offset:32800
	ds_read_b128 v[108:111], v171 offset:32816
	ds_read_b32 v64, v172 offset:0
	ds_read_b32 v65, v172 offset:256
	ds_read_b32 v66, v172 offset:512
	ds_read_b32 v67, v172 offset:768
	ds_read_b32 v68, v172 offset:1024
	ds_read_b32 v69, v172 offset:1280
	ds_read_b32 v70, v172 offset:1536
	ds_read_b32 v71, v172 offset:1792
	ds_read_b32 v72, v172 offset:2048
	ds_read_b32 v73, v172 offset:2304
	ds_read_b32 v74, v172 offset:2560
	s_waitcnt lgkmcnt(11)
	v_lshlrev_b32_e32 v32, 16, v96
	v_and_b32_e32 v33, 0xffff0000, v96
	v_lshlrev_b32_e32 v34, 16, v97
	v_and_b32_e32 v35, 0xffff0000, v97
	v_lshlrev_b32_e32 v36, 16, v98
	v_and_b32_e32 v37, 0xffff0000, v98
	v_lshlrev_b32_e32 v38, 16, v99
	v_and_b32_e32 v39, 0xffff0000, v99
	v_lshlrev_b32_e32 v40, 16, v100
	v_and_b32_e32 v41, 0xffff0000, v100
	v_lshlrev_b32_e32 v42, 16, v101
	v_and_b32_e32 v43, 0xffff0000, v101
	v_lshlrev_b32_e32 v44, 16, v102
	v_and_b32_e32 v45, 0xffff0000, v102
	v_lshlrev_b32_e32 v46, 16, v103
	v_and_b32_e32 v47, 0xffff0000, v103
	v_lshlrev_b32_e32 v48, 16, v104
	v_and_b32_e32 v49, 0xffff0000, v104
	v_lshlrev_b32_e32 v50, 16, v105
	v_and_b32_e32 v51, 0xffff0000, v105
	v_lshlrev_b32_e32 v52, 16, v106
	v_and_b32_e32 v53, 0xffff0000, v106
	v_lshlrev_b32_e32 v54, 16, v107
	v_and_b32_e32 v55, 0xffff0000, v107
	v_lshlrev_b32_e32 v56, 16, v108
	v_and_b32_e32 v57, 0xffff0000, v108
	v_lshlrev_b32_e32 v58, 16, v109
	v_and_b32_e32 v59, 0xffff0000, v109
	v_lshlrev_b32_e32 v60, 16, v110
	v_and_b32_e32 v61, 0xffff0000, v110
	v_lshlrev_b32_e32 v62, 16, v111
	v_and_b32_e32 v63, 0xffff0000, v111
	s_waitcnt lgkmcnt(0)
	ds_read_b32 v75, v172 offset:2816
	ds_read_b32 v76, v172 offset:3072
	ds_read_b32 v77, v172 offset:3328
	ds_read_b32 v78, v172 offset:3584
	ds_read_b32 v79, v172 offset:3840
	ds_read_b32 v80, v172 offset:4096
	ds_read_b32 v81, v172 offset:4352
	ds_read_b32 v82, v172 offset:4608
	ds_read_b32 v83, v172 offset:4864
	ds_read_b32 v84, v172 offset:5120
	ds_read_b32 v85, v172 offset:5376
	ds_read_b32 v86, v172 offset:5632
	ds_read_b32 v87, v172 offset:5888
	ds_read_b32 v88, v172 offset:6144
	ds_read_b32 v89, v172 offset:6400
	v_mfma_f32_32x32x2_f32 v[16:31], v32, v64, 0
	v_mfma_f32_32x32x2_f32 v[16:31], v33, v65, v[16:31]
	v_mfma_f32_32x32x2_f32 v[16:31], v34, v66, v[16:31]
	v_mfma_f32_32x32x2_f32 v[16:31], v35, v67, v[16:31]
	v_mfma_f32_32x32x2_f32 v[16:31], v36, v68, v[16:31]
	v_mfma_f32_32x32x2_f32 v[16:31], v37, v69, v[16:31]
	v_mfma_f32_32x32x2_f32 v[16:31], v38, v70, v[16:31]
	v_mfma_f32_32x32x2_f32 v[16:31], v39, v71, v[16:31]
	v_mfma_f32_32x32x2_f32 v[16:31], v40, v72, v[16:31]
	v_mfma_f32_32x32x2_f32 v[16:31], v41, v73, v[16:31]
	v_mfma_f32_32x32x2_f32 v[16:31], v42, v74, v[16:31]
	s_waitcnt lgkmcnt(0)
	ds_read_b32 v90, v172 offset:6656
	ds_read_b32 v91, v172 offset:6912
	ds_read_b32 v92, v172 offset:7168
	ds_read_b32 v93, v172 offset:7424
	ds_read_b32 v94, v172 offset:7680
	ds_read_b32 v95, v172 offset:7936
	v_mfma_f32_32x32x2_f32 v[16:31], v43, v75, v[16:31]
	v_mfma_f32_32x32x2_f32 v[16:31], v44, v76, v[16:31]
	v_mfma_f32_32x32x2_f32 v[16:31], v45, v77, v[16:31]
	v_mfma_f32_32x32x2_f32 v[16:31], v46, v78, v[16:31]
	v_mfma_f32_32x32x2_f32 v[16:31], v47, v79, v[16:31]
	v_mfma_f32_32x32x2_f32 v[16:31], v48, v80, v[16:31]
	v_mfma_f32_32x32x2_f32 v[16:31], v49, v81, v[16:31]
	v_mfma_f32_32x32x2_f32 v[16:31], v50, v82, v[16:31]
	v_mfma_f32_32x32x2_f32 v[16:31], v51, v83, v[16:31]
	v_mfma_f32_32x32x2_f32 v[16:31], v52, v84, v[16:31]
	v_mfma_f32_32x32x2_f32 v[16:31], v53, v85, v[16:31]
	v_mfma_f32_32x32x2_f32 v[16:31], v54, v86, v[16:31]
	v_mfma_f32_32x32x2_f32 v[16:31], v55, v87, v[16:31]
	v_mfma_f32_32x32x2_f32 v[16:31], v56, v88, v[16:31]
	v_mfma_f32_32x32x2_f32 v[16:31], v57, v89, v[16:31]
	s_waitcnt lgkmcnt(0)
	v_mfma_f32_32x32x2_f32 v[16:31], v58, v90, v[16:31]
	v_mfma_f32_32x32x2_f32 v[16:31], v59, v91, v[16:31]
	v_mfma_f32_32x32x2_f32 v[16:31], v60, v92, v[16:31]
	v_mfma_f32_32x32x2_f32 v[16:31], v61, v93, v[16:31]
	v_mfma_f32_32x32x2_f32 v[16:31], v62, v94, v[16:31]
	v_mfma_f32_32x32x2_f32 v[16:31], v63, v95, v[16:31]
	ds_read_u16 v96, v174 offset:60416
	ds_read_u16 v97, v174 offset:60560
	ds_read_u16 v98, v174 offset:60704
	ds_read_u16 v99, v174 offset:60848
	ds_read_u16 v100, v174 offset:61568
	ds_read_u16 v101, v174 offset:61712
	ds_read_u16 v102, v174 offset:61856
	ds_read_u16 v103, v174 offset:62000
	ds_read_u16 v104, v174 offset:62720
	ds_read_u16 v105, v174 offset:62864
	ds_read_u16 v106, v174 offset:63008
	ds_read_u16 v107, v174 offset:63152
	ds_read_u16 v108, v174 offset:63872
	ds_read_u16 v109, v174 offset:64016
	ds_read_u16 v110, v174 offset:64160
	ds_read_u16 v111, v174 offset:64304
	s_waitcnt lgkmcnt(0)
	s_nop 7
	s_nop 7
	s_nop 3
	v_lshlrev_b32_e32 v96, 16, v96
	v_lshlrev_b32_e32 v97, 16, v97
	v_lshlrev_b32_e32 v98, 16, v98
	v_lshlrev_b32_e32 v99, 16, v99
	v_lshlrev_b32_e32 v100, 16, v100
	v_lshlrev_b32_e32 v101, 16, v101
	v_lshlrev_b32_e32 v102, 16, v102
	v_lshlrev_b32_e32 v103, 16, v103
	v_lshlrev_b32_e32 v104, 16, v104
	v_lshlrev_b32_e32 v105, 16, v105
	v_lshlrev_b32_e32 v106, 16, v106
	v_lshlrev_b32_e32 v107, 16, v107
	v_lshlrev_b32_e32 v108, 16, v108
	v_lshlrev_b32_e32 v109, 16, v109
	v_lshlrev_b32_e32 v110, 16, v110
	v_lshlrev_b32_e32 v111, 16, v111
	v_sub_f32_e32 v96, v96, v16
	v_sub_f32_e32 v97, v97, v17
	v_sub_f32_e32 v98, v98, v18
	v_sub_f32_e32 v99, v99, v19
	v_sub_f32_e32 v100, v100, v20
	v_sub_f32_e32 v101, v101, v21
	v_sub_f32_e32 v102, v102, v22
	v_sub_f32_e32 v103, v103, v23
	v_sub_f32_e32 v104, v104, v24
	v_sub_f32_e32 v105, v105, v25
	v_sub_f32_e32 v106, v106, v26
	v_sub_f32_e32 v107, v107, v27
	v_sub_f32_e32 v108, v108, v28
	v_sub_f32_e32 v109, v109, v29
	v_sub_f32_e32 v110, v110, v30
	v_sub_f32_e32 v111, v111, v31
	ds_write_b32 v173, v96 offset:16384
	ds_write_b32 v173, v97 offset:16640
	ds_write_b32 v173, v98 offset:16896
	ds_write_b32 v173, v99 offset:17152
	ds_write_b32 v173, v100 offset:18432
	ds_write_b32 v173, v101 offset:18688
	ds_write_b32 v173, v102 offset:18944
	ds_write_b32 v173, v103 offset:19200
	ds_write_b32 v173, v104 offset:20480
	ds_write_b32 v173, v105 offset:20736
	ds_write_b32 v173, v106 offset:20992
	ds_write_b32 v173, v107 offset:21248
	ds_write_b32 v173, v108 offset:22528
	ds_write_b32 v173, v109 offset:22784
	ds_write_b32 v173, v110 offset:23040
	ds_write_b32 v173, v111 offset:23296
	s_waitcnt lgkmcnt(0)
	s_barrier
	ds_write_b128 v170, v[144:147] offset:32768
	ds_write_b128 v170, v[148:151] offset:32784
	s_cmp_eq_u32 s12, 32
	s_cbranch_scc1 .Ldq_nopf2
	s_nop 1
	global_load_dwordx4 v[144:147], v169, s[2:3]
	global_load_dwordx4 v[148:151], v169, s[2:3] offset:16
	s_add_u32 s2, s2, 0xa000
	s_addc_u32 s3, s3, 0
	s_add_u32 s4, s4, 4
	s_addc_u32 s5, s5, 0
	s_add_u32 s10, s10, 0x48000
	s_addc_u32 s11, s11, 0
.Ldq_nopf2:
	ds_read_b128 v[96:99], v171 offset:41984
	ds_read_b128 v[100:103], v171 offset:42000
	ds_read_b128 v[104:107], v171 offset:42016
	ds_read_b128 v[108:111], v171 offset:42032
	ds_read_b32 v64, v172 offset:0
	ds_read_b32 v65, v172 offset:256
	ds_read_b32 v66, v172 offset:512
	ds_read_b32 v67, v172 offset:768
	ds_read_b32 v68, v172 offset:1024
	ds_read_b32 v69, v172 offset:1280
	ds_read_b32 v70, v172 offset:1536
	ds_read_b32 v71, v172 offset:1792
	ds_read_b32 v72, v172 offset:2048
	ds_read_b32 v73, v172 offset:2304
	ds_read_b32 v74, v172 offset:2560
	s_waitcnt lgkmcnt(11)
	v_lshlrev_b32_e32 v32, 16, v96
	v_and_b32_e32 v33, 0xffff0000, v96
	v_lshlrev_b32_e32 v34, 16, v97
	v_and_b32_e32 v35, 0xffff0000, v97
	v_lshlrev_b32_e32 v36, 16, v98
	v_and_b32_e32 v37, 0xffff0000, v98
	v_lshlrev_b32_e32 v38, 16, v99
	v_and_b32_e32 v39, 0xffff0000, v99
	v_lshlrev_b32_e32 v40, 16, v100
	v_and_b32_e32 v41, 0xffff0000, v100
	v_lshlrev_b32_e32 v42, 16, v101
	v_and_b32_e32 v43, 0xffff0000, v101
	v_lshlrev_b32_e32 v44, 16, v102
	v_and_b32_e32 v45, 0xffff0000, v102
	v_lshlrev_b32_e32 v46, 16, v103
	v_and_b32_e32 v47, 0xffff0000, v103
	v_lshlrev_b32_e32 v48, 16, v104
	v_and_b32_e32 v49, 0xffff0000, v104
	v_lshlrev_b32_e32 v50, 16, v105
	v_and_b32_e32 v51, 0xffff0000, v105
	v_lshlrev_b32_e32 v52, 16, v106
	v_and_b32_e32 v53, 0xffff0000, v106
	v_lshlrev_b32_e32 v54, 16, v107
	v_and_b32_e32 v55, 0xffff0000, v107
	v_lshlrev_b32_e32 v56, 16, v108
	v_and_b32_e32 v57, 0xffff0000, v108
	v_lshlrev_b32_e32 v58, 16, v109
	v_and_b32_e32 v59, 0xffff0000, v109
	v_lshlrev_b32_e32 v60, 16, v110
	v_and_b32_e32 v61, 0xffff0000, v110
	v_lshlrev_b32_e32 v62, 16, v111
	v_and_b32_e32 v63, 0xffff0000, v111
	s_waitcnt lgkmcnt(0)
	ds_read_b32 v75, v172 offset:2816
	ds_read_b32 v76, v172 offset:3072
	ds_read_b32 v77, v172 offset:3328
	ds_read_b32 v78, v172 offset:3584
	ds_read_b32 v79, v172 offset:3840
	ds_read_b32 v80, v172 offset:4096
	ds_read_b32 v81, v172 offset:4352
	ds_read_b32 v82, v172 offset:4608
	ds_read_b32 v83, v172 offset:4864
	ds_read_b32 v84, v172 offset:5120
	ds_read_b32 v85, v172 offset:5376
	ds_read_b32 v86, v172 offset:5632
	ds_read_b32 v87, v172 offset:5888
	ds_read_b32 v88, v172 offset:6144
	ds_read_b32 v89, v172 offset:6400
	v_mfma_f32_32x32x2_f32 v[16:31], v32, v64, 0
	v_mfma_f32_32x32x2_f32 v[16:31], v33, v65, v[16:31]
	v_mfma_f32_32x32x2_f32 v[16:31], v34, v66, v[16:31]
	v_mfma_f32_32x32x2_f32 v[16:31], v35, v67, v[16:31]
	v_mfma_f32_32x32x2_f32 v[16:31], v36, v68, v[16:31]
	v_mfma_f32_32x32x2_f32 v[16:31], v37, v69, v[16:31]
	v_mfma_f32_32x32x2_f32 v[16:31], v38, v70, v[16:31]
	v_mfma_f32_32x32x2_f32 v[16:31], v39, v71, v[16:31]
	v_mfma_f32_32x32x2_f32 v[16:31], v40, v72, v[16:31]
	v_mfma_f32_32x32x2_f32 v[16:31], v41, v73, v[16:31]
	v_mfma_f32_32x32x2_f32 v[16:31], v42, v74, v[16:31]
	s_waitcnt lgkmcnt(0)
	ds_read_b32 v90, v172 offset:6656
	ds_read_b32 v91, v172 offset:6912
	ds_read_b32 v92, v172 offset:7168
	ds_read_b32 v93, v172 offset:7424
	ds_read_b32 v94, v172 offset:7680
	ds_read_b32 v95, v172 offset:7936
	v_mfma_f32_32x32x2_f32 v[16:31], v43, v75, v[16:31]
	v_mfma_f32_32x32x2_f32 v[16:31], v44, v76, v[16:31]
	v_mfma_f32_32x32x2_f32 v[16:31], v45, v77, v[16:31]
	v_mfma_f32_32x32x2_f32 v[16:31], v46, v78, v[16:31]
	v_mfma_f32_32x32x2_f32 v[16:31], v47, v79, v[16:31]
	v_mfma_f32_32x32x2_f32 v[16:31], v48, v80, v[16:31]
	v_mfma_f32_32x32x2_f32 v[16:31], v49, v81, v[16:31]
	v_mfma_f32_32x32x2_f32 v[16:31], v50, v82, v[16:31]
	v_mfma_f32_32x32x2_f32 v[16:31], v51, v83, v[16:31]
	v_mfma_f32_32x32x2_f32 v[16:31], v52, v84, v[16:31]
	v_mfma_f32_32x32x2_f32 v[16:31], v53, v85, v[16:31]
	v_mfma_f32_32x32x2_f32 v[16:31], v54, v86, v[16:31]
	v_mfma_f32_32x32x2_f32 v[16:31], v55, v87, v[16:31]
	v_mfma_f32_32x32x2_f32 v[16:31], v56, v88, v[16:31]
	v_mfma_f32_32x32x2_f32 v[16:31], v57, v89, v[16:31]
	s_waitcnt lgkmcnt(0)
	v_mfma_f32_32x32x2_f32 v[16:31], v58, v90, v[16:31]
	v_mfma_f32_32x32x2_f32 v[16:31], v59, v91, v[16:31]
	v_mfma_f32_32x32x2_f32 v[16:31], v60, v92, v[16:31]
	v_mfma_f32_32x32x2_f32 v[16:31], v61, v93, v[16:31]
	v_mfma_f32_32x32x2_f32 v[16:31], v62, v94, v[16:31]
	v_mfma_f32_32x32x2_f32 v[16:31], v63, v95, v[16:31]
	ds_read_b128 v[96:99], v171 offset:51200
	ds_read_b128 v[100:103], v171 offset:51216
	ds_read_b128 v[104:107], v171 offset:51232
	ds_read_b128 v[108:111], v171 offset:51248
	ds_read_b32 v64, v172 offset:16384
	ds_read_b32 v65, v172 offset:16640
	ds_read_b32 v66, v172 offset:16896
	ds_read_b32 v67, v172 offset:17152
	ds_read_b32 v68, v172 offset:17408
	ds_read_b32 v69, v172 offset:17664
	ds_read_b32 v70, v172 offset:17920
	ds_read_b32 v71, v172 offset:18176
	ds_read_b32 v72, v172 offset:18432
	ds_read_b32 v73, v172 offset:18688
	ds_read_b32 v74, v172 offset:18944
	s_waitcnt lgkmcnt(11)
	v_lshlrev_b32_e32 v32, 16, v96
	v_and_b32_e32 v33, 0xffff0000, v96
	v_lshlrev_b32_e32 v34, 16, v97
	v_and_b32_e32 v35, 0xffff0000, v97
	v_lshlrev_b32_e32 v36, 16, v98
	v_and_b32_e32 v37, 0xffff0000, v98
	v_lshlrev_b32_e32 v38, 16, v99
	v_and_b32_e32 v39, 0xffff0000, v99
	v_lshlrev_b32_e32 v40, 16, v100
	v_and_b32_e32 v41, 0xffff0000, v100
	v_lshlrev_b32_e32 v42, 16, v101
	v_and_b32_e32 v43, 0xffff0000, v101
	v_lshlrev_b32_e32 v44, 16, v102
	v_and_b32_e32 v45, 0xffff0000, v102
	v_lshlrev_b32_e32 v46, 16, v103
	v_and_b32_e32 v47, 0xffff0000, v103
	v_lshlrev_b32_e32 v48, 16, v104
	v_and_b32_e32 v49, 0xffff0000, v104
	v_lshlrev_b32_e32 v50, 16, v105
	v_and_b32_e32 v51, 0xffff0000, v105
	v_lshlrev_b32_e32 v52, 16, v106
	v_and_b32_e32 v53, 0xffff0000, v106
	v_lshlrev_b32_e32 v54, 16, v107
	v_and_b32_e32 v55, 0xffff0000, v107
	v_lshlrev_b32_e32 v56, 16, v108
	v_and_b32_e32 v57, 0xffff0000, v108
	v_lshlrev_b32_e32 v58, 16, v109
	v_and_b32_e32 v59, 0xffff0000, v109
	v_lshlrev_b32_e32 v60, 16, v110
	v_and_b32_e32 v61, 0xffff0000, v110
	v_lshlrev_b32_e32 v62, 16, v111
	v_and_b32_e32 v63, 0xffff0000, v111
	s_waitcnt lgkmcnt(0)
	ds_read_b32 v75, v172 offset:19200
	ds_read_b32 v76, v172 offset:19456
	ds_read_b32 v77, v172 offset:19712
	ds_read_b32 v78, v172 offset:19968
	ds_read_b32 v79, v172 offset:20224
	ds_read_b32 v80, v172 offset:20480
	ds_read_b32 v81, v172 offset:20736
	ds_read_b32 v82, v172 offset:20992
	ds_read_b32 v83, v172 offset:21248
	ds_read_b32 v84, v172 offset:21504
	ds_read_b32 v85, v172 offset:21760
	ds_read_b32 v86, v172 offset:22016
	ds_read_b32 v87, v172 offset:22272
	ds_read_b32 v88, v172 offset:22528
	ds_read_b32 v89, v172 offset:22784
	v_mfma_f32_32x32x2_f32 v[16:31], v32, v64, v[16:31]
	v_mfma_f32_32x32x2_f32 v[16:31], v33, v65, v[16:31]
	v_mfma_f32_32x32x2_f32 v[16:31], v34, v66, v[16:31]
	v_mfma_f32_32x32x2_f32 v[16:31], v35, v67, v[16:31]
	v_mfma_f32_32x32x2_f32 v[16:31], v36, v68, v[16:31]
	v_mfma_f32_32x32x2_f32 v[16:31], v37, v69, v[16:31]
	v_mfma_f32_32x32x2_f32 v[16:31], v38, v70, v[16:31]
	v_mfma_f32_32x32x2_f32 v[16:31], v39, v71, v[16:31]
	v_mfma_f32_32x32x2_f32 v[16:31], v40, v72, v[16:31]
	v_mfma_f32_32x32x2_f32 v[16:31], v41, v73, v[16:31]
	v_mfma_f32_32x32x2_f32 v[16:31], v42, v74, v[16:31]
	s_waitcnt lgkmcnt(0)
	ds_read_b32 v90, v172 offset:23040
	ds_read_b32 v91, v172 offset:23296
	ds_read_b32 v92, v172 offset:23552
	ds_read_b32 v93, v172 offset:23808
	ds_read_b32 v94, v172 offset:24064
	ds_read_b32 v95, v172 offset:24320
	v_mfma_f32_32x32x2_f32 v[16:31], v43, v75, v[16:31]
	v_mfma_f32_32x32x2_f32 v[16:31], v44, v76, v[16:31]
	v_mfma_f32_32x32x2_f32 v[16:31], v45, v77, v[16:31]
	v_mfma_f32_32x32x2_f32 v[16:31], v46, v78, v[16:31]
	v_mfma_f32_32x32x2_f32 v[16:31], v47, v79, v[16:31]
	v_mfma_f32_32x32x2_f32 v[16:31], v48, v80, v[16:31]
	v_mfma_f32_32x32x2_f32 v[16:31], v49, v81, v[16:31]
	v_mfma_f32_32x32x2_f32 v[16:31], v50, v82, v[16:31]
	v_mfma_f32_32x32x2_f32 v[16:31], v51, v83, v[16:31]
	v_mfma_f32_32x32x2_f32 v[16:31], v52, v84, v[16:31]
	v_mfma_f32_32x32x2_f32 v[16:31], v53, v85, v[16:31]
	v_mfma_f32_32x32x2_f32 v[16:31], v54, v86, v[16:31]
	v_mfma_f32_32x32x2_f32 v[16:31], v55, v87, v[16:31]
	v_mfma_f32_32x32x2_f32 v[16:31], v56, v88, v[16:31]
	v_mfma_f32_32x32x2_f32 v[16:31], v57, v89, v[16:31]
	s_waitcnt lgkmcnt(0)
	v_mfma_f32_32x32x2_f32 v[16:31], v58, v90, v[16:31]
	v_mfma_f32_32x32x2_f32 v[16:31], v59, v91, v[16:31]
	v_mfma_f32_32x32x2_f32 v[16:31], v60, v92, v[16:31]
	v_mfma_f32_32x32x2_f32 v[16:31], v61, v93, v[16:31]
	v_mfma_f32_32x32x2_f32 v[16:31], v62, v94, v[16:31]
	v_mfma_f32_32x32x2_f32 v[16:31], v63, v95, v[16:31]
	s_waitcnt lgkmcnt(0)
	s_barrier
	s_nop 7
	s_nop 7
	s_nop 3
	ds_write_b32 v173, v16 offset:41984
	ds_write_b32 v173, v17 offset:42240
	ds_write_b32 v173, v18 offset:42496
	ds_write_b32 v173, v19 offset:42752
	ds_write_b32 v173, v20 offset:44032
	ds_write_b32 v173, v21 offset:44288
	ds_write_b32 v173, v22 offset:44544
	ds_write_b32 v173, v23 offset:44800
	ds_write_b32 v173, v24 offset:46080
	ds_write_b32 v173, v25 offset:46336
	ds_write_b32 v173, v26 offset:46592
	ds_write_b32 v173, v27 offset:46848
	ds_write_b32 v173, v28 offset:48128
	ds_write_b32 v173, v29 offset:48384
	ds_write_b32 v173, v30 offset:48640
	ds_write_b32 v173, v31 offset:48896
	ds_read_b128 v[96:99], v171 offset:32768
	ds_read_b128 v[100:103], v171 offset:32784
	ds_read_b128 v[104:107], v171 offset:32800
	ds_read_b128 v[108:111], v171 offset:32816
	ds_read_b32 v64, v172 offset:16384
	ds_read_b32 v65, v172 offset:16640
	ds_read_b32 v66, v172 offset:16896
	ds_read_b32 v67, v172 offset:17152
	ds_read_b32 v68, v172 offset:17408
	ds_read_b32 v69, v172 offset:17664
	ds_read_b32 v70, v172 offset:17920
	ds_read_b32 v71, v172 offset:18176
	ds_read_b32 v72, v172 offset:18432
	ds_read_b32 v73, v172 offset:18688
	ds_read_b32 v74, v172 offset:18944
	s_waitcnt lgkmcnt(11)
	v_lshlrev_b32_e32 v32, 16, v96
	v_and_b32_e32 v33, 0xffff0000, v96
	v_lshlrev_b32_e32 v34, 16, v97
	v_and_b32_e32 v35, 0xffff0000, v97
	v_lshlrev_b32_e32 v36, 16, v98
	v_and_b32_e32 v37, 0xffff0000, v98
	v_lshlrev_b32_e32 v38, 16, v99
	v_and_b32_e32 v39, 0xffff0000, v99
	v_lshlrev_b32_e32 v40, 16, v100
	v_and_b32_e32 v41, 0xffff0000, v100
	v_lshlrev_b32_e32 v42, 16, v101
	v_and_b32_e32 v43, 0xffff0000, v101
	v_lshlrev_b32_e32 v44, 16, v102
	v_and_b32_e32 v45, 0xffff0000, v102
	v_lshlrev_b32_e32 v46, 16, v103
	v_and_b32_e32 v47, 0xffff0000, v103
	v_lshlrev_b32_e32 v48, 16, v104
	v_and_b32_e32 v49, 0xffff0000, v104
	v_lshlrev_b32_e32 v50, 16, v105
	v_and_b32_e32 v51, 0xffff0000, v105
	v_lshlrev_b32_e32 v52, 16, v106
	v_and_b32_e32 v53, 0xffff0000, v106
	v_lshlrev_b32_e32 v54, 16, v107
	v_and_b32_e32 v55, 0xffff0000, v107
	v_lshlrev_b32_e32 v56, 16, v108
	v_and_b32_e32 v57, 0xffff0000, v108
	v_lshlrev_b32_e32 v58, 16, v109
	v_and_b32_e32 v59, 0xffff0000, v109
	v_lshlrev_b32_e32 v60, 16, v110
	v_and_b32_e32 v61, 0xffff0000, v110
	v_lshlrev_b32_e32 v62, 16, v111
	v_and_b32_e32 v63, 0xffff0000, v111
	s_waitcnt lgkmcnt(0)
	ds_read_b32 v75, v172 offset:19200
	ds_read_b32 v76, v172 offset:19456
	ds_read_b32 v77, v172 offset:19712
	ds_read_b32 v78, v172 offset:19968
	ds_read_b32 v79, v172 offset:20224
	ds_read_b32 v80, v172 offset:20480
	ds_read_b32 v81, v172 offset:20736
	ds_read_b32 v82, v172 offset:20992
	ds_read_b32 v83, v172 offset:21248
	ds_read_b32 v84, v172 offset:21504
	ds_read_b32 v85, v172 offset:21760
	ds_read_b32 v86, v172 offset:22016
	ds_read_b32 v87, v172 offset:22272
	ds_read_b32 v88, v172 offset:22528
	ds_read_b32 v89, v172 offset:22784
	v_mfma_f32_32x32x2_f32 v[16:31], v32, v64, 0
	v_mfma_f32_32x32x2_f32 v[16:31], v33, v65, v[16:31]
	v_mfma_f32_32x32x2_f32 v[16:31], v34, v66, v[16:31]
	v_mfma_f32_32x32x2_f32 v[16:31], v35, v67, v[16:31]
	v_mfma_f32_32x32x2_f32 v[16:31], v36, v68, v[16:31]
	v_mfma_f32_32x32x2_f32 v[16:31], v37, v69, v[16:31]
	v_mfma_f32_32x32x2_f32 v[16:31], v38, v70, v[16:31]
	v_mfma_f32_32x32x2_f32 v[16:31], v39, v71, v[16:31]
	v_mfma_f32_32x32x2_f32 v[16:31], v40, v72, v[16:31]
	v_mfma_f32_32x32x2_f32 v[16:31], v41, v73, v[16:31]
	v_mfma_f32_32x32x2_f32 v[16:31], v42, v74, v[16:31]
	s_waitcnt lgkmcnt(0)
	ds_read_b32 v90, v172 offset:23040
	ds_read_b32 v91, v172 offset:23296
	ds_read_b32 v92, v172 offset:23552
	ds_read_b32 v93, v172 offset:23808
	ds_read_b32 v94, v172 offset:24064
	ds_read_b32 v95, v172 offset:24320
	v_mfma_f32_32x32x2_f32 v[16:31], v43, v75, v[16:31]
	v_mfma_f32_32x32x2_f32 v[16:31], v44, v76, v[16:31]
	v_mfma_f32_32x32x2_f32 v[16:31], v45, v77, v[16:31]
	v_mfma_f32_32x32x2_f32 v[16:31], v46, v78, v[16:31]
	v_mfma_f32_32x32x2_f32 v[16:31], v47, v79, v[16:31]
	v_mfma_f32_32x32x2_f32 v[16:31], v48, v80, v[16:31]
	v_mfma_f32_32x32x2_f32 v[16:31], v49, v81, v[16:31]
	v_mfma_f32_32x32x2_f32 v[16:31], v50, v82, v[16:31]
	v_mfma_f32_32x32x2_f32 v[16:31], v51, v83, v[16:31]
	v_mfma_f32_32x32x2_f32 v[16:31], v52, v84, v[16:31]
	v_mfma_f32_32x32x2_f32 v[16:31], v53, v85, v[16:31]
	v_mfma_f32_32x32x2_f32 v[16:31], v54, v86, v[16:31]
	v_mfma_f32_32x32x2_f32 v[16:31], v55, v87, v[16:31]
	v_mfma_f32_32x32x2_f32 v[16:31], v56, v88, v[16:31]
	v_mfma_f32_32x32x2_f32 v[16:31], v57, v89, v[16:31]
	s_waitcnt lgkmcnt(0)
	v_mfma_f32_32x32x2_f32 v[16:31], v58, v90, v[16:31]
	v_mfma_f32_32x32x2_f32 v[16:31], v59, v91, v[16:31]
	v_mfma_f32_32x32x2_f32 v[16:31], v60, v92, v[16:31]
	v_mfma_f32_32x32x2_f32 v[16:31], v61, v93, v[16:31]
	v_mfma_f32_32x32x2_f32 v[16:31], v62, v94, v[16:31]
	v_mfma_f32_32x32x2_f32 v[16:31], v63, v95, v[16:31]
	s_nop 7
	s_nop 7
	s_nop 3
	v_fma_f32 v0, v164, v0, v16
	v_fma_f32 v1, v164, v1, v17
	v_fma_f32 v2, v164, v2, v18
	v_fma_f32 v3, v164, v3, v19
	v_fma_f32 v4, v164, v4, v20
	v_fma_f32 v5, v164, v5, v21
	v_fma_f32 v6, v164, v6, v22
	v_fma_f32 v7, v164, v7, v23
	v_fma_f32 v8, v164, v8, v24
	v_fma_f32 v9, v164, v9, v25
	v_fma_f32 v10, v164, v10, v26
	v_fma_f32 v11, v164, v11, v27
	v_fma_f32 v12, v164, v12, v28
	v_fma_f32 v13, v164, v13, v29
	v_fma_f32 v14, v164, v14, v30
	v_fma_f32 v15, v164, v15, v31
	ds_write_b32 v173, v0 offset:0
	ds_write_b32 v173, v1 offset:256
	ds_write_b32 v173, v2 offset:512
	ds_write_b32 v173, v3 offset:768
	ds_write_b32 v173, v4 offset:2048
	ds_write_b32 v173, v5 offset:2304
	ds_write_b32 v173, v6 offset:2560
	ds_write_b32 v173, v7 offset:2816
	ds_write_b32 v173, v8 offset:4096
	ds_write_b32 v173, v9 offset:4352
	ds_write_b32 v173, v10 offset:4608
	ds_write_b32 v173, v11 offset:4864
	ds_write_b32 v173, v12 offset:6144
	ds_write_b32 v173, v13 offset:6400
	ds_write_b32 v173, v14 offset:6656
	ds_write_b32 v173, v15 offset:6912
	s_waitcnt lgkmcnt(0)
	s_barrier
	s_cmp_eq_u32 s12, 0
	s_cbranch_scc1 .Ldq_epi3
	ds_read_b128 v[32:35], v175 offset:41984
	s_nop 0
	s_waitcnt lgkmcnt(0)
	s_nop 0
	v_mul_f32_e32 v185, v32, v32
	s_nop 0
	v_fmac_f32_e32 v185, v33, v33
	s_nop 0
	v_fmac_f32_e32 v185, v34, v34
	s_nop 0
	v_fmac_f32_e32 v185, v35, v35
	s_nop 0
	s_nop 1
	s_nop 0
	v_add_f32_dpp v185, v185, v185 quad_perm:[1,0,3,2] row_mask:0xf bank_mask:0xf
	s_nop 0
	s_nop 1
	ds_read_b128 v[36:39], v175 offset:46080
	v_add_f32_dpp v185, v185, v185 quad_perm:[2,3,0,1] row_mask:0xf bank_mask:0xf
	s_waitcnt lgkmcnt(0)
	s_nop 1
	v_mul_f32_e32 v64, v36, v36
	v_add_f32_dpp v185, v185, v185 row_half_mirror row_mask:0xf bank_mask:0xf
	v_fmac_f32_e32 v64, v37, v37
	s_nop 1
	v_fmac_f32_e32 v64, v38, v38
	v_add_f32_dpp v185, v185, v185 row_mirror row_mask:0xf bank_mask:0xf
	v_fmac_f32_e32 v64, v39, v39
	v_mov_b32_e32 v186, 0x358637bd
	s_nop 1
	v_fmac_f32_e32 v186, 0x3c800000, v185
	v_add_f32_dpp v64, v64, v64 quad_perm:[1,0,3,2] row_mask:0xf bank_mask:0xf
	v_rsq_f32_e32 v186, v186
	s_nop 1
	s_nop 0
	v_add_f32_dpp v64, v64, v64 quad_perm:[2,3,0,1] row_mask:0xf bank_mask:0xf
	v_mul_f32_e32 v32, v32, v186
	s_nop 1
	v_mul_f32_e32 v33, v33, v186
	v_add_f32_dpp v64, v64, v64 row_half_mirror row_mask:0xf bank_mask:0xf
	v_mul_f32_e32 v34, v34, v186
	s_nop 1
	v_mul_f32_e32 v35, v35, v186
	v_add_f32_dpp v64, v64, v64 row_mirror row_mask:0xf bank_mask:0xf
	v_mul_f32_e32 v32, v32, v160
	v_mov_b32_e32 v65, 0x358637bd
	v_mul_f32_e32 v33, v33, v161
	v_fmac_f32_e32 v65, 0x3c800000, v64
	v_mul_f32_e32 v34, v34, v162
	v_rsq_f32_e32 v65, v65
	v_mul_f32_e32 v35, v35, v163
	s_nop 0
	v_lshlrev_b32_e32 v187, 16, v152
	v_mul_f32_e32 v36, v36, v65
	v_and_b32_e32 v188, 0xffff0000, v152
	v_mul_f32_e32 v37, v37, v65
	v_lshlrev_b32_e32 v189, 16, v153
	v_mul_f32_e32 v38, v38, v65
	v_and_b32_e32 v190, 0xffff0000, v153
	v_mul_f32_e32 v39, v39, v65
	v_mul_f32_e32 v195, 0xbfb8aa3b, v187
	v_mul_f32_e32 v36, v36, v160
	v_exp_f32_e32 v195, v195
	v_mul_f32_e32 v37, v37, v161
	s_nop 0
	v_mul_f32_e32 v38, v38, v162
	v_add_f32_e32 v195, 1.0, v195
	v_mul_f32_e32 v39, v39, v163
	v_div_scale_f32 v191, s[52:53], v195, v195, v187
	v_lshlrev_b32_e32 v66, 16, v154
	v_rcp_f32_e32 v192, v191
	v_and_b32_e32 v67, 0xffff0000, v154
	s_nop 0
	v_lshlrev_b32_e32 v68, 16, v155
	v_fma_f32 v193, -v191, v192, 1.0
	v_and_b32_e32 v69, 0xffff0000, v155
	v_fmac_f32_e32 v192, v193, v192
	v_mul_f32_e32 v74, 0xbfb8aa3b, v66
	v_div_scale_f32 v193, vcc, v187, v195, v187
	v_exp_f32_e32 v74, v74
	v_mul_f32_e32 v194, v193, v192
	s_nop 0
	v_fma_f32 v196, -v191, v194, v193
	v_add_f32_e32 v74, 1.0, v74
	v_fmac_f32_e32 v194, v196, v192
	v_div_scale_f32 v70, s[52:53], v74, v74, v66
	v_fma_f32 v191, -v191, v194, v193
	v_rcp_f32_e32 v71, v70
	v_div_fmas_f32 v191, v191, v192, v194
	s_nop 0
	v_div_fixup_f32 v191, v191, v195, v187
	v_fma_f32 v72, -v70, v71, 1.0
	v_mul_f32_e32 v32, v32, v191
	v_fmac_f32_e32 v71, v72, v71
	v_mul_f32_e32 v195, 0xbfb8aa3b, v188
	v_div_scale_f32 v72, vcc, v66, v74, v66
	v_exp_f32_e32 v195, v195
	v_mul_f32_e32 v73, v72, v71
	s_nop 0
	v_fma_f32 v75, -v70, v73, v72
	v_add_f32_e32 v195, 1.0, v195
	v_fmac_f32_e32 v73, v75, v71
	v_div_scale_f32 v191, s[52:53], v195, v195, v188
	v_fma_f32 v70, -v70, v73, v72
	v_rcp_f32_e32 v192, v191
	v_div_fmas_f32 v70, v70, v71, v73
	s_nop 0
	v_div_fixup_f32 v70, v70, v74, v66
	v_fma_f32 v193, -v191, v192, 1.0
	v_mul_f32_e32 v36, v36, v70
	v_fmac_f32_e32 v192, v193, v192
	v_mul_f32_e32 v74, 0xbfb8aa3b, v67
	v_div_scale_f32 v193, vcc, v188, v195, v188
	v_exp_f32_e32 v74, v74
	v_mul_f32_e32 v194, v193, v192
	s_nop 0
	v_fma_f32 v196, -v191, v194, v193
	v_add_f32_e32 v74, 1.0, v74
	v_fmac_f32_e32 v194, v196, v192
	v_div_scale_f32 v70, s[52:53], v74, v74, v67
	v_fma_f32 v191, -v191, v194, v193
	v_rcp_f32_e32 v71, v70
	v_div_fmas_f32 v191, v191, v192, v194
	s_nop 0
	v_div_fixup_f32 v191, v191, v195, v188
	v_fma_f32 v72, -v70, v71, 1.0
	v_mul_f32_e32 v33, v33, v191
	v_fmac_f32_e32 v71, v72, v71
	v_mul_f32_e32 v195, 0xbfb8aa3b, v189
	v_div_scale_f32 v72, vcc, v67, v74, v67
	v_exp_f32_e32 v195, v195
	v_mul_f32_e32 v73, v72, v71
	s_nop 0
	v_fma_f32 v75, -v70, v73, v72
	v_add_f32_e32 v195, 1.0, v195
	v_fmac_f32_e32 v73, v75, v71
	v_div_scale_f32 v191, s[52:53], v195, v195, v189
	v_fma_f32 v70, -v70, v73, v72
	v_rcp_f32_e32 v192, v191
	v_div_fmas_f32 v70, v70, v71, v73
	s_nop 0
	v_div_fixup_f32 v70, v70, v74, v67
	v_fma_f32 v193, -v191, v192, 1.0
	v_mul_f32_e32 v37, v37, v70
	v_fmac_f32_e32 v192, v193, v192
	v_mul_f32_e32 v74, 0xbfb8aa3b, v68
	v_div_scale_f32 v193, vcc, v189, v195, v189
	v_exp_f32_e32 v74, v74
	v_mul_f32_e32 v194, v193, v192
	s_nop 0
	v_fma_f32 v196, -v191, v194, v193
	v_add_f32_e32 v74, 1.0, v74
	v_fmac_f32_e32 v194, v196, v192
	v_div_scale_f32 v70, s[52:53], v74, v74, v68
	v_fma_f32 v191, -v191, v194, v193
	v_rcp_f32_e32 v71, v70
	v_div_fmas_f32 v191, v191, v192, v194
	s_nop 0
	v_div_fixup_f32 v191, v191, v195, v189
	v_fma_f32 v72, -v70, v71, 1.0
	v_mul_f32_e32 v34, v34, v191
	v_fmac_f32_e32 v71, v72, v71
	v_mul_f32_e32 v195, 0xbfb8aa3b, v190
	v_div_scale_f32 v72, vcc, v68, v74, v68
	v_exp_f32_e32 v195, v195
	v_mul_f32_e32 v73, v72, v71
	s_nop 0
	v_fma_f32 v75, -v70, v73, v72
	v_add_f32_e32 v195, 1.0, v195
	v_fmac_f32_e32 v73, v75, v71
	v_div_scale_f32 v191, s[52:53], v195, v195, v190
	v_fma_f32 v70, -v70, v73, v72
	v_rcp_f32_e32 v192, v191
	v_div_fmas_f32 v70, v70, v71, v73
	s_nop 0
	v_div_fixup_f32 v70, v70, v74, v68
	v_fma_f32 v193, -v191, v192, 1.0
	v_mul_f32_e32 v38, v38, v70
	v_fmac_f32_e32 v192, v193, v192
	v_mul_f32_e32 v74, 0xbfb8aa3b, v69
	v_div_scale_f32 v193, vcc, v190, v195, v190
	v_exp_f32_e32 v74, v74
	v_mul_f32_e32 v194, v193, v192
	s_nop 0
	v_fma_f32 v196, -v191, v194, v193
	v_add_f32_e32 v74, 1.0, v74
	v_fmac_f32_e32 v194, v196, v192
	v_div_scale_f32 v70, s[52:53], v74, v74, v69
	v_fma_f32 v191, -v191, v194, v193
	v_rcp_f32_e32 v71, v70
	v_div_fmas_f32 v191, v191, v192, v194
	s_nop 0
	v_div_fixup_f32 v191, v191, v195, v190
	v_fma_f32 v72, -v70, v71, 1.0
	v_mul_f32_e32 v35, v35, v191
	v_fmac_f32_e32 v71, v72, v71
	v_bfe_u32 v191, v32, 16, 1
	v_div_scale_f32 v72, vcc, v69, v74, v69
	v_bfe_u32 v192, v33, 16, 1
	v_mul_f32_e32 v73, v72, v71
	v_bfe_u32 v193, v34, 16, 1
	v_fma_f32 v75, -v70, v73, v72
	v_bfe_u32 v194, v35, 16, 1
	v_fmac_f32_e32 v73, v75, v71
	v_add3_u32 v32, v32, v191, s69
	v_fma_f32 v70, -v70, v73, v72
	v_add3_u32 v33, v33, v192, s69
	v_div_fmas_f32 v70, v70, v71, v73
	v_add3_u32 v34, v34, v193, s69
	v_div_fixup_f32 v70, v70, v74, v69
	v_add3_u32 v35, v35, v194, s69
	v_mul_f32_e32 v39, v39, v70
	v_lshrrev_b32_e32 v32, 16, v32
	v_bfe_u32 v70, v36, 16, 1
	v_lshrrev_b32_e32 v34, 16, v34
	v_bfe_u32 v71, v37, 16, 1
	v_and_or_b32 v198, v33, s34, v32
	v_bfe_u32 v72, v38, 16, 1
	v_and_or_b32 v199, v35, s34, v34
	v_bfe_u32 v73, v39, 16, 1
	global_store_dwordx2 v176, v[198:199], s[8:9]
	v_add3_u32 v36, v36, v70, s69
	s_nop 1
	v_add3_u32 v37, v37, v71, s69
	v_add3_u32 v38, v38, v72, s69
	s_nop 0
	v_add3_u32 v39, v39, v73, s69
	s_nop 0
	v_lshrrev_b32_e32 v36, 16, v36
	s_nop 0
	v_lshrrev_b32_e32 v38, 16, v38
	s_nop 0
	v_and_or_b32 v76, v37, s34, v36
	s_nop 0
	v_and_or_b32 v77, v39, s34, v38
	s_nop 0
	global_store_dwordx2 v177, v[76:77], s[8:9]
	s_nop 0
	s_nop 1
	s_nop 0
	ds_read_b128 v[40:43], v175 offset:50176
	s_nop 0
	s_waitcnt lgkmcnt(0)
	s_nop 0
	v_mul_f32_e32 v185, v40, v40
	s_nop 0
	v_fmac_f32_e32 v185, v41, v41
	s_nop 0
	v_fmac_f32_e32 v185, v42, v42
	s_nop 0
	v_fmac_f32_e32 v185, v43, v43
	s_nop 0
	s_nop 1
	s_nop 0
	v_add_f32_dpp v185, v185, v185 quad_perm:[1,0,3,2] row_mask:0xf bank_mask:0xf
	s_nop 0
	s_nop 1
	ds_read_b128 v[44:47], v175 offset:54272
	v_add_f32_dpp v185, v185, v185 quad_perm:[2,3,0,1] row_mask:0xf bank_mask:0xf
	s_waitcnt lgkmcnt(0)
	s_nop 1
	v_mul_f32_e32 v64, v44, v44
	v_add_f32_dpp v185, v185, v185 row_half_mirror row_mask:0xf bank_mask:0xf
	v_fmac_f32_e32 v64, v45, v45
	s_nop 1
	v_fmac_f32_e32 v64, v46, v46
	v_add_f32_dpp v185, v185, v185 row_mirror row_mask:0xf bank_mask:0xf
	v_fmac_f32_e32 v64, v47, v47
	v_mov_b32_e32 v186, 0x358637bd
	s_nop 1
	v_fmac_f32_e32 v186, 0x3c800000, v185
	v_add_f32_dpp v64, v64, v64 quad_perm:[1,0,3,2] row_mask:0xf bank_mask:0xf
	v_rsq_f32_e32 v186, v186
	s_nop 1
	s_nop 0
	v_add_f32_dpp v64, v64, v64 quad_perm:[2,3,0,1] row_mask:0xf bank_mask:0xf
	v_mul_f32_e32 v40, v40, v186
	s_nop 1
	v_mul_f32_e32 v41, v41, v186
	v_add_f32_dpp v64, v64, v64 row_half_mirror row_mask:0xf bank_mask:0xf
	v_mul_f32_e32 v42, v42, v186
	s_nop 1
	v_mul_f32_e32 v43, v43, v186
	v_add_f32_dpp v64, v64, v64 row_mirror row_mask:0xf bank_mask:0xf
	v_mul_f32_e32 v40, v40, v160
	v_mov_b32_e32 v65, 0x358637bd
	v_mul_f32_e32 v41, v41, v161
	v_fmac_f32_e32 v65, 0x3c800000, v64
	v_mul_f32_e32 v42, v42, v162
	v_rsq_f32_e32 v65, v65
	v_mul_f32_e32 v43, v43, v163
	s_nop 0
	v_lshlrev_b32_e32 v187, 16, v156
	v_mul_f32_e32 v44, v44, v65
	v_and_b32_e32 v188, 0xffff0000, v156
	v_mul_f32_e32 v45, v45, v65
	v_lshlrev_b32_e32 v189, 16, v157
	v_mul_f32_e32 v46, v46, v65
	v_and_b32_e32 v190, 0xffff0000, v157
	v_mul_f32_e32 v47, v47, v65
	v_mul_f32_e32 v195, 0xbfb8aa3b, v187
	v_mul_f32_e32 v44, v44, v160
	v_exp_f32_e32 v195, v195
	v_mul_f32_e32 v45, v45, v161
	s_nop 0
	v_mul_f32_e32 v46, v46, v162
	v_add_f32_e32 v195, 1.0, v195
	v_mul_f32_e32 v47, v47, v163
	v_div_scale_f32 v191, s[52:53], v195, v195, v187
	v_lshlrev_b32_e32 v66, 16, v158
	v_rcp_f32_e32 v192, v191
	v_and_b32_e32 v67, 0xffff0000, v158
	s_nop 0
	v_lshlrev_b32_e32 v68, 16, v159
	v_fma_f32 v193, -v191, v192, 1.0
	v_and_b32_e32 v69, 0xffff0000, v159
	v_fmac_f32_e32 v192, v193, v192
	v_mul_f32_e32 v74, 0xbfb8aa3b, v66
	v_div_scale_f32 v193, vcc, v187, v195, v187
	v_exp_f32_e32 v74, v74
	v_mul_f32_e32 v194, v193, v192
	s_nop 0
	v_fma_f32 v196, -v191, v194, v193
	v_add_f32_e32 v74, 1.0, v74
	v_fmac_f32_e32 v194, v196, v192
	v_div_scale_f32 v70, s[52:53], v74, v74, v66
	v_fma_f32 v191, -v191, v194, v193
	v_rcp_f32_e32 v71, v70
	v_div_fmas_f32 v191, v191, v192, v194
	s_nop 0
	v_div_fixup_f32 v191, v191, v195, v187
	v_fma_f32 v72, -v70, v71, 1.0
	v_mul_f32_e32 v40, v40, v191
	v_fmac_f32_e32 v71, v72, v71
	v_mul_f32_e32 v195, 0xbfb8aa3b, v188
	v_div_scale_f32 v72, vcc, v66, v74, v66
	v_exp_f32_e32 v195, v195
	v_mul_f32_e32 v73, v72, v71
	s_nop 0
	v_fma_f32 v75, -v70, v73, v72
	v_add_f32_e32 v195, 1.0, v195
	v_fmac_f32_e32 v73, v75, v71
	v_div_scale_f32 v191, s[52:53], v195, v195, v188
	v_fma_f32 v70, -v70, v73, v72
	v_rcp_f32_e32 v192, v191
	v_div_fmas_f32 v70, v70, v71, v73
	s_nop 0
	v_div_fixup_f32 v70, v70, v74, v66
	v_fma_f32 v193, -v191, v192, 1.0
	v_mul_f32_e32 v44, v44, v70
	v_fmac_f32_e32 v192, v193, v192
	v_mul_f32_e32 v74, 0xbfb8aa3b, v67
	v_div_scale_f32 v193, vcc, v188, v195, v188
	v_exp_f32_e32 v74, v74
	v_mul_f32_e32 v194, v193, v192
	s_nop 0
	v_fma_f32 v196, -v191, v194, v193
	v_add_f32_e32 v74, 1.0, v74
	v_fmac_f32_e32 v194, v196, v192
	v_div_scale_f32 v70, s[52:53], v74, v74, v67
	v_fma_f32 v191, -v191, v194, v193
	v_rcp_f32_e32 v71, v70
	v_div_fmas_f32 v191, v191, v192, v194
	s_nop 0
	v_div_fixup_f32 v191, v191, v195, v188
	v_fma_f32 v72, -v70, v71, 1.0
	v_mul_f32_e32 v41, v41, v191
	v_fmac_f32_e32 v71, v72, v71
	v_mul_f32_e32 v195, 0xbfb8aa3b, v189
	v_div_scale_f32 v72, vcc, v67, v74, v67
	v_exp_f32_e32 v195, v195
	v_mul_f32_e32 v73, v72, v71
	s_nop 0
	v_fma_f32 v75, -v70, v73, v72
	v_add_f32_e32 v195, 1.0, v195
	v_fmac_f32_e32 v73, v75, v71
	v_div_scale_f32 v191, s[52:53], v195, v195, v189
	v_fma_f32 v70, -v70, v73, v72
	v_rcp_f32_e32 v192, v191
	v_div_fmas_f32 v70, v70, v71, v73
	s_nop 0
	v_div_fixup_f32 v70, v70, v74, v67
	v_fma_f32 v193, -v191, v192, 1.0
	v_mul_f32_e32 v45, v45, v70
	v_fmac_f32_e32 v192, v193, v192
	v_mul_f32_e32 v74, 0xbfb8aa3b, v68
	v_div_scale_f32 v193, vcc, v189, v195, v189
	v_exp_f32_e32 v74, v74
	v_mul_f32_e32 v194, v193, v192
	s_nop 0
	v_fma_f32 v196, -v191, v194, v193
	v_add_f32_e32 v74, 1.0, v74
	v_fmac_f32_e32 v194, v196, v192
	v_div_scale_f32 v70, s[52:53], v74, v74, v68
	v_fma_f32 v191, -v191, v194, v193
	v_rcp_f32_e32 v71, v70
	v_div_fmas_f32 v191, v191, v192, v194
	s_nop 0
	v_div_fixup_f32 v191, v191, v195, v189
	v_fma_f32 v72, -v70, v71, 1.0
	v_mul_f32_e32 v42, v42, v191
	v_fmac_f32_e32 v71, v72, v71
	v_mul_f32_e32 v195, 0xbfb8aa3b, v190
	v_div_scale_f32 v72, vcc, v68, v74, v68
	v_exp_f32_e32 v195, v195
	v_mul_f32_e32 v73, v72, v71
	s_nop 0
	v_fma_f32 v75, -v70, v73, v72
	v_add_f32_e32 v195, 1.0, v195
	v_fmac_f32_e32 v73, v75, v71
	v_div_scale_f32 v191, s[52:53], v195, v195, v190
	v_fma_f32 v70, -v70, v73, v72
	v_rcp_f32_e32 v192, v191
	v_div_fmas_f32 v70, v70, v71, v73
	s_nop 0
	v_div_fixup_f32 v70, v70, v74, v68
	v_fma_f32 v193, -v191, v192, 1.0
	v_mul_f32_e32 v46, v46, v70
	v_fmac_f32_e32 v192, v193, v192
	v_mul_f32_e32 v74, 0xbfb8aa3b, v69
	v_div_scale_f32 v193, vcc, v190, v195, v190
	v_exp_f32_e32 v74, v74
	v_mul_f32_e32 v194, v193, v192
	s_nop 0
	v_fma_f32 v196, -v191, v194, v193
	v_add_f32_e32 v74, 1.0, v74
	v_fmac_f32_e32 v194, v196, v192
	v_div_scale_f32 v70, s[52:53], v74, v74, v69
	v_fma_f32 v191, -v191, v194, v193
	v_rcp_f32_e32 v71, v70
	v_div_fmas_f32 v191, v191, v192, v194
	s_nop 0
	v_div_fixup_f32 v191, v191, v195, v190
	v_fma_f32 v72, -v70, v71, 1.0
	v_mul_f32_e32 v43, v43, v191
	v_fmac_f32_e32 v71, v72, v71
	v_bfe_u32 v191, v40, 16, 1
	v_div_scale_f32 v72, vcc, v69, v74, v69
	v_bfe_u32 v192, v41, 16, 1
	v_mul_f32_e32 v73, v72, v71
	v_bfe_u32 v193, v42, 16, 1
	v_fma_f32 v75, -v70, v73, v72
	v_bfe_u32 v194, v43, 16, 1
	v_fmac_f32_e32 v73, v75, v71
	v_add3_u32 v40, v40, v191, s69
	v_fma_f32 v70, -v70, v73, v72
	v_add3_u32 v41, v41, v192, s69
	v_div_fmas_f32 v70, v70, v71, v73
	v_add3_u32 v42, v42, v193, s69
	v_div_fixup_f32 v70, v70, v74, v69
	v_add3_u32 v43, v43, v194, s69
	v_mul_f32_e32 v47, v47, v70
	v_lshrrev_b32_e32 v40, 16, v40
	v_bfe_u32 v70, v44, 16, 1
	v_lshrrev_b32_e32 v42, 16, v42
	v_bfe_u32 v71, v45, 16, 1
	v_and_or_b32 v198, v41, s34, v40
	v_bfe_u32 v72, v46, 16, 1
	v_and_or_b32 v199, v43, s34, v42
	v_bfe_u32 v73, v47, 16, 1
	global_store_dwordx2 v178, v[198:199], s[8:9]
	v_add3_u32 v44, v44, v70, s69
	s_nop 1
	v_add3_u32 v45, v45, v71, s69
	v_add3_u32 v46, v46, v72, s69
	s_nop 0
	v_add3_u32 v47, v47, v73, s69
	s_nop 0
	v_lshrrev_b32_e32 v44, 16, v44
	s_nop 0
	v_lshrrev_b32_e32 v46, 16, v46
	s_nop 0
	v_and_or_b32 v76, v45, s34, v44
	s_nop 0
	v_and_or_b32 v77, v47, s34, v46
	s_nop 0
	global_store_dwordx2 v179, v[76:77], s[8:9]
	s_nop 0
	s_nop 1
	s_nop 0
	s_waitcnt vmcnt(4)
	s_branch .Ldq_epid
